# c41 + gemm1 K-loop edge: next tile's stage select, LDS/DMA base addresses and m0 computed before the closing vmcnt wait and barrier instead of at the post-barrier loop head
# baseline (speedup 1.0000x reference)
; #define LDSAS __attribute__((address_space(3)))
; #define G_ISSUE(kt, st) do { G_ISSUE1(kt, st, 0); G_ISSUE1(kt, st, 1); G_ISSUE1(kt, st, 2); G_ISSUE1(kt, st, 3); } while (0)
; template <bool LOWREG = false>
; __device__ __forceinline__ void gemm_core(const bf16_t* __restrict__ A, int lda, const bf16_t* __restrict__ Bt, int ldb, int K, f32x4 (&acc)[8][4], unsigned char* smem, int tid) {
;     asm volatile("" : "+v"(tid));
;     const int lane = tid & 63, w = __builtin_amdgcn_readfirstlane(tid >> 6), wm = w >> 2, wn = w & 3, idx = lane & 15, kq = lane >> 4;
;     unsigned offA[4], offB[4];
; #pragma unroll
;     for (int j = 0; j < 4; ++j) { const int row = (j * 8 + w) * 8 + (lane >> 3), c = (lane & 7) ^ ((row >> 1) & 7);
;         offA[j] = (unsigned)(row * lda + c * 8) * 2u; offB[j] = (unsigned)(row * ldb + c * 8) * 2u; }
; #pragma unroll
;     for (int mi = 0; mi < 8; ++mi)
; #pragma unroll
;         for (int ni = 0; ni < 4; ++ni) acc[mi][ni] = (f32x4){0.f, 0.f, 0.f, 0.f};
;     LDSAS unsigned char* lds = (LDSAS unsigned char*)smem;
;     ...
;     const int nk = K >> 6;
;     G_ISSUE(0, 0);
;     asm volatile("s_waitcnt vmcnt(0)" ::: "memory");
;     __syncthreads();
;     const int swz = (idx >> 1) & 7;
;     const int aoff = (wm * 128 + idx) * 128, boff = G_AB + (wn * 64 + idx) * 128;
;     for (int kt = 0; kt < nk; ++kt) {
;         const int st = kt & 1;
;         const bool more = kt + 1 < nk;
;         const unsigned char* sb = smem + st * G_STAGE;
; __device__ void gemm1_phase(const Params& p, int l, int hb, unsigned char* smem) {
;     ...
;     for (int t = blockIdx.x; t < NTILES; t += gridDim.x) {
;         const int grp = t / GRP, r = t % GRP, jx = NT * (r & 7) + (r >> 3), mt = grp * 8 + (jx & 7), nt = jx >> 3;
;         const int m0 = mt * 256, n0 = nt * 256;
;         f32x4 acc[8][4];
;         int tid = threadIdx.x;
;         gemm_core(H + (size_t)m0 * 1024, 1024, Wt + (size_t)n0 * 1024, 1024, 1024, acc, smem, tid);
.Lg1_nosplit:
	s_mul_hi_i32 s9, s99, 0x78787879
	s_lshr_b32 s11, s9, 31
	s_ashr_i32 s9, s9, 7
	s_add_i32 s9, s9, s11
	s_mul_i32 s11, s9, 0x110
	s_sub_i32 s11, s99, s11
	s_and_b32 s12, s11, 7
	s_mul_i32 s12, s12, 34
	s_ashr_i32 s11, s11, 3
	s_add_i32 s12, s12, s11
	s_lshl_b32 s11, s12, 8
	s_lshl_b32 s9, s9, 11
	s_and_b32 s11, s11, 0x700
	s_or_b32 s56, s11, s9
	s_lshr_b32 s36, s12, 3
	s_lshr_b32 s11, s9, 11
	s_mul_i32 s11, s11, 5
	s_add_i32 s36, s36, s11
	s_mul_i32 s11, s36, 1928
	s_lshr_b32 s11, s11, 16
	s_mul_i32 s11, s11, 34
	s_sub_i32 s36, s36, s11
	s_lshl_b32 s36, s36, 8
	s_mov_b32 s11, s36
	s_ashr_i32 s57, s56, 31
	s_lshl_b64 s[16:17], s[56:57], 11
	s_add_u32 s18, s92, s16
	s_addc_u32 s19, s93, s17
	s_ashr_i32 s37, s36, 31
	s_lshl_b64 s[20:21], s[36:37], 11
	v_mov_b32_e32 v0, v210
	s_add_u32 s22, s94, s20
	s_addc_u32 s23, s95, s21
	v_readfirstlane_b32 s12, v0
	s_ashr_i32 s24, s12, 6
	s_and_b32 s101, s24, 3
	s_cmp_lg_u32 s101, 0
	s_cselect_b32 s101, 1, 2
	s_cmp_eq_u32 s36, 0x2100
	s_cselect_b32 s101, s101, 0
	s_lshr_b32 s98, s24, 2
	s_cmp_lg_u32 s98, s100
	s_cselect_b32 s98, 1, 0
	s_cmp_lt_i32 s100, 0
	s_cselect_b32 s98, 0, s98
	s_or_b32 s101, s101, s98
	v_bfe_u32 v2, v0, 3, 3
	v_lshl_or_b32 v3, s24, 3, v2
	v_lshrrev_b32_e32 v4, 1, v3
	v_xor_b32_e32 v4, v4, v0
	v_lshlrev_b32_e32 v4, 4, v4
	s_lshl_b32 s9, s24, 10
	v_and_b32_e32 v4, 0x70, v4
	s_add_i32 s9, s9, 0
	v_lshl_or_b32 v3, v3, 11, v4
	s_mov_b32 m0, s9
	v_add_u32_e32 v5, 0x20000, v3
	global_load_lds_dwordx4 v3, s[18:19]
	s_add_i32 m0, s9, 0x8000
	v_add_u32_e32 v6, 0x40000, v3
	global_load_lds_dwordx4 v3, s[22:23]
	s_add_i32 m0, s9, 0x2000
	v_add_u32_e32 v7, 0x60000, v3
	global_load_lds_dwordx4 v5, s[18:19]
	s_add_i32 m0, s9, 0xa000
	v_and_b32_e32 v1, 15, v0
	global_load_lds_dwordx4 v5, s[22:23]
	s_add_i32 m0, s9, 0x4000
	v_bfe_u32 v8, v0, 4, 2
	global_load_lds_dwordx4 v6, s[18:19]
	s_add_i32 m0, s9, 0xc000
	v_lshrrev_b32_e32 v3, 1, v0
	global_load_lds_dwordx4 v6, s[22:23]
	s_add_i32 m0, s9, 0x6000
	v_bfe_u32 v0, v0, 1, 3
	global_load_lds_dwordx4 v7, s[18:19]
	s_add_i32 m0, s9, 0xe000
	s_lshr_b32 s18, s12, 1
	global_load_lds_dwordx4 v7, s[22:23]
	s_and_b32 s18, s18, 0x1ffff80
	s_and_b32 s12, s12, 0xc0
	v_or_b32_e32 v5, s18, v1
	v_or_b32_e32 v1, s12, v1
	s_lshl_b32 s12, s24, 14
	s_add_u32 s16, s96, s16
	v_lshlrev_b32_e32 v149, 7, v5
	v_bitop3_b32 v0, v8, v0, 4 bitop3:0x36
	v_lshlrev_b32_e32 v5, 11, v2
	s_addc_u32 s17, s97, s17
	s_add_i32 s18, s12, 0x20000
	v_lshlrev_b32_e32 v147, 7, v1
	v_bitop3_b32 v1, v8, v3, 7 bitop3:0x78
	v_lshlrev_b32_e32 v146, 4, v0
	v_or3_b32 v80, s12, v5, v4
	v_or3_b32 v0, s18, v5, v4
	s_add_i32 s18, s12, 0x40000
	s_add_i32 s12, s12, 0x60000
	v_lshlrev_b32_e32 v148, 4, v1
	v_mov_b32_e32 v1, v81
	v_or3_b32 v2, s18, v5, v4
	v_mov_b32_e32 v3, v81
	v_or3_b32 v4, s12, v5, v4
	v_mov_b32_e32 v5, v81
	v_lshl_add_u64 v[130:131], s[16:17], 0, v[80:81]
	v_lshl_add_u64 v[132:133], s[16:17], 0, v[0:1]
	v_lshl_add_u64 v[134:135], s[16:17], 0, v[2:3]
	v_lshl_add_u64 v[136:137], s[16:17], 0, v[4:5]
	s_add_u32 s16, s64, s20
	s_waitcnt vmcnt(0)
	s_addc_u32 s17, s65, s21
	v_lshl_add_u64 v[140:141], s[16:17], 0, v[0:1]
	v_mov_b32_e32 v0, 0
	v_lshl_add_u64 v[138:139], s[16:17], 0, v[80:81]
	v_lshl_add_u64 v[142:143], s[16:17], 0, v[2:3]
	v_lshl_add_u64 v[144:145], s[16:17], 0, v[4:5]
	s_mov_b32 s12, 0
	s_mov_b64 s[38:39], 0
	v_mov_b32_e32 v1, v0
	v_mov_b32_e32 v2, v0
	v_mov_b32_e32 v3, v0
	v_mov_b32_e32 v4, v0
	v_mov_b32_e32 v5, v0
	v_mov_b32_e32 v6, v0
	v_mov_b32_e32 v7, v0
	v_mov_b32_e32 v8, v0
	v_mov_b32_e32 v9, v0
	s_waitcnt vmcnt(0)
	v_mov_b32_e32 v10, v0
	v_mov_b32_e32 v11, v0
	v_mov_b32_e32 v12, v0
	v_mov_b32_e32 v13, v0
	v_mov_b32_e32 v14, v0
	v_mov_b32_e32 v15, v0
	v_mov_b32_e32 v16, v0
	v_mov_b32_e32 v17, v0
	v_mov_b32_e32 v18, v0
	v_mov_b32_e32 v19, v0
	v_mov_b32_e32 v20, v0
	v_mov_b32_e32 v21, v0
	v_mov_b32_e32 v22, v0
	v_mov_b32_e32 v23, v0
	v_mov_b32_e32 v24, v0
	v_mov_b32_e32 v25, v0
	v_mov_b32_e32 v26, v0
	v_mov_b32_e32 v27, v0
	v_mov_b32_e32 v28, v0
	v_mov_b32_e32 v29, v0
	v_mov_b32_e32 v30, v0
	v_mov_b32_e32 v31, v0
	v_mov_b32_e32 v32, v0
	v_mov_b32_e32 v33, v0
	v_mov_b32_e32 v34, v0
	v_mov_b32_e32 v35, v0
	v_mov_b32_e32 v36, v0
	v_mov_b32_e32 v37, v0
	v_mov_b32_e32 v38, v0
	v_mov_b32_e32 v39, v0
	v_mov_b32_e32 v40, v0
	v_mov_b32_e32 v41, v0
	v_mov_b32_e32 v42, v0
	v_mov_b32_e32 v43, v0
	v_mov_b32_e32 v44, v0
	v_mov_b32_e32 v45, v0
	v_mov_b32_e32 v46, v0
	v_mov_b32_e32 v47, v0
	v_mov_b32_e32 v48, v0
	v_mov_b32_e32 v49, v0
	v_mov_b32_e32 v50, v0
	v_mov_b32_e32 v51, v0
	v_mov_b32_e32 v52, v0
	v_mov_b32_e32 v53, v0
	v_mov_b32_e32 v54, v0
	v_mov_b32_e32 v55, v0
	v_mov_b32_e32 v56, v0
	v_mov_b32_e32 v57, v0
	v_mov_b32_e32 v58, v0
	v_mov_b32_e32 v59, v0
	v_mov_b32_e32 v60, v0
	v_mov_b32_e32 v61, v0
	v_mov_b32_e32 v62, v0
	v_mov_b32_e32 v63, v0
	v_mov_b32_e32 v64, v0
	v_mov_b32_e32 v65, v0
	v_mov_b32_e32 v66, v0
	v_mov_b32_e32 v67, v0
	v_mov_b32_e32 v68, v0
	v_mov_b32_e32 v69, v0
	v_mov_b32_e32 v70, v0
	v_mov_b32_e32 v71, v0
	v_mov_b32_e32 v72, v0
	v_mov_b32_e32 v73, v0
	v_mov_b32_e32 v74, v0
	v_mov_b32_e32 v75, v0
	v_mov_b32_e32 v76, v0
	v_mov_b32_e32 v77, v0
	v_mov_b32_e32 v78, v0
	v_mov_b32_e32 v79, v0
	v_mov_b32_e32 v82, v0
	v_mov_b32_e32 v83, v0
	v_mov_b32_e32 v84, v0
	v_mov_b32_e32 v85, v0
	v_mov_b32_e32 v86, v0
	v_mov_b32_e32 v87, v0
	v_mov_b32_e32 v88, v0
	v_mov_b32_e32 v89, v0
	v_mov_b32_e32 v90, v0
	v_mov_b32_e32 v91, v0
	v_mov_b32_e32 v92, v0
	v_mov_b32_e32 v93, v0
	v_mov_b32_e32 v94, v0
	v_mov_b32_e32 v95, v0
	v_mov_b32_e32 v96, v0
	v_mov_b32_e32 v97, v0
	v_mov_b32_e32 v98, v0
	v_mov_b32_e32 v99, v0
	v_mov_b32_e32 v100, v0
	v_mov_b32_e32 v101, v0
	v_mov_b32_e32 v102, v0
	v_mov_b32_e32 v103, v0
	v_mov_b32_e32 v104, v0
	v_mov_b32_e32 v105, v0
	v_mov_b32_e32 v106, v0
	v_mov_b32_e32 v107, v0
	v_mov_b32_e32 v108, v0
	v_mov_b32_e32 v109, v0
	v_mov_b32_e32 v110, v0
	v_mov_b32_e32 v111, v0
	v_mov_b32_e32 v112, v0
	v_mov_b32_e32 v113, v0
	v_mov_b32_e32 v114, v0
	v_mov_b32_e32 v115, v0
	v_mov_b32_e32 v116, v0
	v_mov_b32_e32 v117, v0
	v_mov_b32_e32 v118, v0
	v_mov_b32_e32 v119, v0
	v_mov_b32_e32 v120, v0
	v_mov_b32_e32 v121, v0
	v_mov_b32_e32 v122, v0
	v_mov_b32_e32 v123, v0
	v_mov_b32_e32 v124, v0
	v_mov_b32_e32 v125, v0
	v_mov_b32_e32 v126, v0
	v_mov_b32_e32 v127, v0
	v_mov_b32_e32 v128, v0
	v_mov_b32_e32 v129, v0
	s_waitcnt lgkmcnt(0)
	s_barrier
	s_and_b32 s16, s12, 0x10000
	s_add_i32 s17, s16, 0
	s_xor_b32 s16, s16, 0x10000
	s_add_i32 s16, s9, s16
	v_add_u32_e32 v80, s17, v147
	v_add_u32_e32 v179, s17, v149
	v_lshl_add_u64 v[200:201], v[130:131], 0, s[38:39]
	s_mov_b32 m0, s16
; template <bool LOWREG = false>
; __device__ __forceinline__ void gemm_core(const bf16_t* __restrict__ A, int lda, const bf16_t* __restrict__ Bt, int ldb, int K, f32x4 (&acc)[8][4], unsigned char* smem, int tid) {
;     ...
;         const unsigned char* sb = smem + st * G_STAGE;
;         if constexpr (!LOWREG) {
; #pragma unroll
;         for (int ks = 0; ks < 2; ++ks) {
;             bf16x8 bfr[4], af[8];
;             const int co = ((ks * 4 + kq) ^ swz) * 16;
; #pragma unroll
;             for (int ni = 0; ni < 4; ++ni) bfr[ni] = *(const bf16x8*)(sb + boff + ni * 2048 + co);
; #pragma unroll
;             for (int mi = 0; mi < 8; ++mi) af[mi] = *(const bf16x8*)(sb + aoff + mi * 2048 + co);
;             if (more) { G_ISSUE1(kt + 1, st ^ 1, ks * 2); G_ISSUE1(kt + 1, st ^ 1, ks * 2 + 1); }
;             __builtin_amdgcn_sched_barrier(0);
;             __builtin_amdgcn_s_setprio(1);
; #pragma unroll
;             for (int mi = 0; mi < 8; ++mi)
; #pragma unroll
;                 for (int ni = 0; ni < 4; ++ni) acc[mi][ni] = __builtin_amdgcn_mfma_f32_16x16x32_bf16(bfr[ni], af[mi], acc[mi][ni], 0, 0, 0);
;             __builtin_amdgcn_s_setprio(0);
;             __builtin_amdgcn_sched_barrier(0);
;         }
.LBB0_255:
	v_add_u32_e32 v162, v80, v148
	v_add_u32_e32 v196, v179, v148
	ds_read_b128 v[150:153], v162 offset:32768
	ds_read_b128 v[154:157], v162 offset:34816
	ds_read_b128 v[158:161], v162 offset:36864
	ds_read_b128 v[162:165], v162 offset:38912
	ds_read_b128 v[166:169], v196
	ds_read_b128 v[170:173], v196 offset:2048
	ds_read_b128 v[174:177], v196 offset:4096
	ds_read_b128 v[180:183], v196 offset:6144
	ds_read_b128 v[184:187], v196 offset:8192
	ds_read_b128 v[188:191], v196 offset:10240
	ds_read_b128 v[192:195], v196 offset:12288
	ds_read_b128 v[196:199], v196 offset:14336
	global_load_lds_dwordx4 v[200:201], off
	v_lshl_add_u64 v[200:201], v[138:139], 0, s[38:39]
	s_add_i32 m0, s16, 0x8000
	s_nop 0
	global_load_lds_dwordx4 v[200:201], off
	v_lshl_add_u64 v[200:201], v[132:133], 0, s[38:39]
	s_add_i32 m0, s16, 0x2000
	s_nop 0
	global_load_lds_dwordx4 v[200:201], off
	v_lshl_add_u64 v[200:201], v[140:141], 0, s[38:39]
	s_add_i32 m0, s16, 0xa000
	s_nop 0
	global_load_lds_dwordx4 v[200:201], off
	s_cmp_lg_u32 s101, 0
	s_cbranch_scc1 .Lg1_dtalt1
	s_setprio 1
	s_waitcnt lgkmcnt(0)
	v_mfma_f32_16x16x32_bf16 v[126:129], v[150:153], v[166:169], v[126:129]
	v_mfma_f32_16x16x32_bf16 v[122:125], v[154:157], v[166:169], v[122:125]
	v_mfma_f32_16x16x32_bf16 v[118:121], v[158:161], v[166:169], v[118:121]
	v_mfma_f32_16x16x32_bf16 v[114:117], v[162:165], v[166:169], v[114:117]
	v_mfma_f32_16x16x32_bf16 v[110:113], v[150:153], v[170:173], v[110:113]
	v_mfma_f32_16x16x32_bf16 v[106:109], v[154:157], v[170:173], v[106:109]
	v_mfma_f32_16x16x32_bf16 v[102:105], v[158:161], v[170:173], v[102:105]
	v_mfma_f32_16x16x32_bf16 v[98:101], v[162:165], v[170:173], v[98:101]
	v_mfma_f32_16x16x32_bf16 v[94:97], v[150:153], v[174:177], v[94:97]
	v_mfma_f32_16x16x32_bf16 v[90:93], v[154:157], v[174:177], v[90:93]
	v_mfma_f32_16x16x32_bf16 v[86:89], v[158:161], v[174:177], v[86:89]
	v_mfma_f32_16x16x32_bf16 v[82:85], v[162:165], v[174:177], v[82:85]
	v_mfma_f32_16x16x32_bf16 v[76:79], v[150:153], v[180:183], v[76:79]
	v_mfma_f32_16x16x32_bf16 v[72:75], v[154:157], v[180:183], v[72:75]
	v_mfma_f32_16x16x32_bf16 v[68:71], v[158:161], v[180:183], v[68:71]
	v_mfma_f32_16x16x32_bf16 v[64:67], v[162:165], v[180:183], v[64:67]
	v_mfma_f32_16x16x32_bf16 v[60:63], v[150:153], v[184:187], v[60:63]
	v_mfma_f32_16x16x32_bf16 v[56:59], v[154:157], v[184:187], v[56:59]
	v_mfma_f32_16x16x32_bf16 v[52:55], v[158:161], v[184:187], v[52:55]
	v_mfma_f32_16x16x32_bf16 v[48:51], v[162:165], v[184:187], v[48:51]
	v_mfma_f32_16x16x32_bf16 v[44:47], v[150:153], v[188:191], v[44:47]
	v_mfma_f32_16x16x32_bf16 v[40:43], v[154:157], v[188:191], v[40:43]
	v_mfma_f32_16x16x32_bf16 v[36:39], v[158:161], v[188:191], v[36:39]
	v_mfma_f32_16x16x32_bf16 v[32:35], v[162:165], v[188:191], v[32:35]
	v_mfma_f32_16x16x32_bf16 v[28:31], v[150:153], v[192:195], v[28:31]
	v_mfma_f32_16x16x32_bf16 v[24:27], v[154:157], v[192:195], v[24:27]
	v_mfma_f32_16x16x32_bf16 v[20:23], v[158:161], v[192:195], v[20:23]
	v_mfma_f32_16x16x32_bf16 v[16:19], v[162:165], v[192:195], v[16:19]
	v_mfma_f32_16x16x32_bf16 v[12:15], v[150:153], v[196:199], v[12:15]
	v_mfma_f32_16x16x32_bf16 v[8:11], v[154:157], v[196:199], v[8:11]
	v_mfma_f32_16x16x32_bf16 v[4:7], v[158:161], v[196:199], v[4:7]
	v_mfma_f32_16x16x32_bf16 v[0:3], v[162:165], v[196:199], v[0:3]
	s_setprio 0

; template <bool LOWREG = false>
; __device__ __forceinline__ void gemm_core(const bf16_t* __restrict__ A, int lda, const bf16_t* __restrict__ Bt, int ldb, int K, f32x4 (&acc)[8][4], unsigned char* smem, int tid) {
;     ...
;     for (int kt = 0; kt < nk; ++kt) {
;         const int st = kt & 1;
;         const bool more = kt + 1 < nk;
;         const unsigned char* sb = smem + st * G_STAGE;
;         if constexpr (!LOWREG) {
; #pragma unroll
;         for (int ks = 0; ks < 2; ++ks) {
;             bf16x8 bfr[4], af[8];
;             const int co = ((ks * 4 + kq) ^ swz) * 16;
; #pragma unroll
;             for (int ni = 0; ni < 4; ++ni) bfr[ni] = *(const bf16x8*)(sb + boff + ni * 2048 + co);
; #pragma unroll
;             for (int mi = 0; mi < 8; ++mi) af[mi] = *(const bf16x8*)(sb + aoff + mi * 2048 + co);
;             if (more) { G_ISSUE1(kt + 1, st ^ 1, ks * 2); G_ISSUE1(kt + 1, st ^ 1, ks * 2 + 1); }
;             __builtin_amdgcn_sched_barrier(0);
;             __builtin_amdgcn_s_setprio(1);
; #pragma unroll
;             for (int mi = 0; mi < 8; ++mi)
; #pragma unroll
;                 for (int ni = 0; ni < 4; ++ni) acc[mi][ni] = __builtin_amdgcn_mfma_f32_16x16x32_bf16(bfr[ni], af[mi], acc[mi][ni], 0, 0, 0);
;             __builtin_amdgcn_s_setprio(0);
;             __builtin_amdgcn_sched_barrier(0);
;         }
;         } else {
; #pragma unroll
;         for (int ks = 0; ks < 2; ++ks) {
;             bf16x8 bfr[4];
;             const int co = ((ks * 4 + kq) ^ swz) * 16;
; #pragma unroll
;             for (int ni = 0; ni < 4; ++ni) bfr[ni] = *(const bf16x8*)(sb + boff + ni * 2048 + co);
; #pragma unroll
;             for (int mh = 0; mh < 2; ++mh) {
;                 bf16x8 af[4];
; #pragma unroll
;                 for (int mi = 0; mi < 4; ++mi) af[mi] = *(const bf16x8*)(sb + aoff + (mh * 4 + mi) * 2048 + co);
;                 if (more) G_ISSUE1(kt + 1, st ^ 1, ks * 2 + mh);
;                 __builtin_amdgcn_sched_barrier(0);
;                 __builtin_amdgcn_s_setprio(1);
; #pragma unroll
;                 for (int mi = 0; mi < 4; ++mi)
; #pragma unroll
;                     for (int ni = 0; ni < 4; ++ni) acc[mh * 4 + mi][ni] = __builtin_amdgcn_mfma_f32_16x16x32_bf16(bfr[ni], af[mi], acc[mh * 4 + mi][ni], 0, 0, 0);
;                 __builtin_amdgcn_s_setprio(0);
;                 __builtin_amdgcn_sched_barrier(0);
;             }
;         }
.Lg1_dtskip2:
	s_waitcnt lgkmcnt(0)
	s_add_i32 s12, s12, 0x10000
	s_add_u32 s38, s38, 0x80
	s_addc_u32 s39, s39, 0
	s_and_b32 s16, s12, 0x10000
	s_add_i32 s17, s16, 0
	s_xor_b32 s16, s16, 0x10000
	s_add_i32 s16, s9, s16
	v_add_u32_e32 v80, s17, v147
	v_add_u32_e32 v179, s17, v149
	v_lshl_add_u64 v[200:201], v[130:131], 0, s[38:39]
	s_mov_b32 m0, s16
	s_waitcnt vmcnt(0)
	s_cmpk_lg_i32 s38, 0x780
	s_waitcnt vmcnt(0)
	s_barrier
	s_cbranch_scc1 .LBB0_255
	s_add_i32 s9, 0, 0x10000
	v_add_u32_e32 v80, s9, v149
	v_add_u32_e32 v149, v80, v148
	ds_read_b128 v[130:133], v149 offset:14336
	ds_read_b128 v[134:137], v149 offset:12288
	ds_read_b128 v[138:141], v149 offset:10240
	ds_read_b128 v[142:145], v149 offset:8192
	ds_read_b128 v[150:153], v149 offset:6144
	ds_read_b128 v[154:157], v149 offset:4096
	ds_read_b128 v[158:161], v149 offset:2048
	ds_read_b128 v[162:165], v149
	v_add_u32_e32 v147, s9, v147
	v_add_u32_e32 v148, v147, v148
	ds_read_b128 v[166:169], v148 offset:38912
	ds_read_b128 v[170:173], v148 offset:36864
	ds_read_b128 v[174:177], v148 offset:34816
	ds_read_b128 v[180:183], v148 offset:32768
	s_cmp_lg_u32 s101, 0
	s_cbranch_scc1 .Lg1_dtalt3
	s_setprio 1
	s_waitcnt lgkmcnt(0)
	v_mfma_f32_16x16x32_bf16 v[126:129], v[180:183], v[162:165], v[126:129]
	v_mfma_f32_16x16x32_bf16 v[122:125], v[174:177], v[162:165], v[122:125]
	v_mfma_f32_16x16x32_bf16 v[118:121], v[170:173], v[162:165], v[118:121]
	v_mfma_f32_16x16x32_bf16 v[114:117], v[166:169], v[162:165], v[114:117]
	v_mfma_f32_16x16x32_bf16 v[110:113], v[180:183], v[158:161], v[110:113]
	v_mfma_f32_16x16x32_bf16 v[106:109], v[174:177], v[158:161], v[106:109]
	v_mfma_f32_16x16x32_bf16 v[102:105], v[170:173], v[158:161], v[102:105]
	v_mfma_f32_16x16x32_bf16 v[98:101], v[166:169], v[158:161], v[98:101]
	v_mfma_f32_16x16x32_bf16 v[94:97], v[180:183], v[154:157], v[94:97]
	v_mfma_f32_16x16x32_bf16 v[90:93], v[174:177], v[154:157], v[90:93]
	v_mfma_f32_16x16x32_bf16 v[86:89], v[170:173], v[154:157], v[86:89]
	v_mfma_f32_16x16x32_bf16 v[82:85], v[166:169], v[154:157], v[82:85]
	v_mfma_f32_16x16x32_bf16 v[76:79], v[180:183], v[150:153], v[76:79]
	v_mfma_f32_16x16x32_bf16 v[72:75], v[174:177], v[150:153], v[72:75]
	v_mfma_f32_16x16x32_bf16 v[68:71], v[170:173], v[150:153], v[68:71]
	v_mfma_f32_16x16x32_bf16 v[64:67], v[166:169], v[150:153], v[64:67]
	v_mfma_f32_16x16x32_bf16 v[60:63], v[180:183], v[142:145], v[60:63]
	v_mfma_f32_16x16x32_bf16 v[56:59], v[174:177], v[142:145], v[56:59]
	v_mfma_f32_16x16x32_bf16 v[52:55], v[170:173], v[142:145], v[52:55]
	v_mfma_f32_16x16x32_bf16 v[48:51], v[166:169], v[142:145], v[48:51]
	v_mfma_f32_16x16x32_bf16 v[44:47], v[180:183], v[138:141], v[44:47]
	v_mfma_f32_16x16x32_bf16 v[40:43], v[174:177], v[138:141], v[40:43]
	v_mfma_f32_16x16x32_bf16 v[36:39], v[170:173], v[138:141], v[36:39]
	v_mfma_f32_16x16x32_bf16 v[32:35], v[166:169], v[138:141], v[32:35]
	v_mfma_f32_16x16x32_bf16 v[28:31], v[180:183], v[134:137], v[28:31]
	v_mfma_f32_16x16x32_bf16 v[24:27], v[174:177], v[134:137], v[24:27]
	v_mfma_f32_16x16x32_bf16 v[20:23], v[170:173], v[134:137], v[20:23]
	v_mfma_f32_16x16x32_bf16 v[16:19], v[166:169], v[134:137], v[16:19]
	v_mfma_f32_16x16x32_bf16 v[12:15], v[180:183], v[130:133], v[12:15]
	v_mfma_f32_16x16x32_bf16 v[8:11], v[174:177], v[130:133], v[8:11]
	v_mfma_f32_16x16x32_bf16 v[4:7], v[170:173], v[130:133], v[4:7]
	v_mfma_f32_16x16x32_bf16 v[0:3], v[166:169], v[130:133], v[0:3]
	s_setprio 0
